# split P2->P3 grid barrier: arrive, then P3 set-up + one statically assigned dilated-attention unit per CU (needs no P2 data) in the barrier shadow, then wait + redo set-up; dynamic queue shortened by
# speedup vs baseline: 1.0133x; 1.0133x over previous
.LBB0_250:
	v_readlane_b32 s4, v254, 49
	s_add_i32 s14, s4, 3
	v_readlane_b32 s4, v252, 9
	v_readlane_b32 s5, v252, 10
	s_cmp_ge_i32 s14, s5
	s_cbranch_scc1 .LBB0_304
	s_waitcnt vmcnt(0)
	s_waitcnt lgkmcnt(0)
	s_barrier
	s_cmp_lg_u32 s3, 0x100
	s_cbranch_scc1 .Lxb2_full
	s_mov_b64 s[4:5], exec
	v_readlane_b32 s6, v252, 31
	v_readlane_b32 s7, v252, 32
	s_mul_i32 s72, s62, 5
	s_add_i32 s72, s72, 3
	s_and_b64 s[6:7], s[4:5], s[6:7]
	s_mov_b64 exec, s[6:7]
	s_cbranch_execz .Lxb2s_done
	v_readlane_b32 s10, v253, 57
	v_readlane_b32 s11, v253, 58
	v_readlane_b32 s73, v254, 38
	v_mov_b32_e32 v2, 1
	s_nop 4
	global_atomic_add v3, v1, v2, s[10:11] sc0
	v_mov_b32_e32 v0, s73
	v_readlane_b32 s73, v254, 39
	ds_read_b32 v4, v0
	s_nop 1
	v_mov_b32_e32 v0, s73
	ds_read_b32 v5, v0
	s_waitcnt lgkmcnt(0)
	v_mul_lo_u32 v4, v4, s72
	v_mul_lo_u32 v5, v5, s72
	s_waitcnt vmcnt(0)
	v_add_u32_e32 v3, 1, v3
	v_cmp_eq_u32_e32 vcc, v3, v4
	s_cbranch_vccz .Lxb2s_done
	buffer_wbl2 sc1
	v_readlane_b32 s10, v253, 61
	v_readlane_b32 s11, v253, 62
	s_waitcnt vmcnt(0)
	s_nop 4
	global_atomic_add v3, v1, v2, s[10:11] sc0
	s_waitcnt vmcnt(0)
	v_add_u32_e32 v3, 1, v3
	v_cmp_eq_u32_e32 vcc, v3, v5
	s_cbranch_vccz .Lxb2s_done
	s_add_u32 s10, s30, 0x8400
	s_addc_u32 s11, s31, 0
	s_mov_b64 exec, -1
	v_mbcnt_lo_u32_b32 v3, -1, 0
	v_mbcnt_hi_u32_b32 v3, -1, v3
	s_sub_u32 s73, s72, 1
	v_mov_b32_e32 v2, s73
	v_lshlrev_b32_e32 v3, 5, v3
	s_nop 1
	global_store_dword v3, v2, s[10:11] sc0 sc1
	global_store_dword v3, v2, s[10:11] offset:2048 sc0 sc1
	s_add_u32 s10, s10, 0x1000
	s_addc_u32 s11, s11, 0
	global_store_dword v3, v2, s[10:11] sc0 sc1
	global_store_dword v3, v2, s[10:11] offset:2048 sc0 sc1
	s_mov_b64 exec, s[6:7]
.Lxb2s_done:
	s_or_b64 exec, exec, s[4:5]
	s_mov_b32 s6, 1
	s_nop 1
	v_writelane_b32 v255, s6, 41
	s_branch .LBB0_304
.Lxb2_full:
	s_mov_b32 s6, 0
	s_nop 1
	v_writelane_b32 v255, s6, 41
	s_mov_b64 s[4:5], exec
	v_readlane_b32 s6, v252, 31
	v_readlane_b32 s7, v252, 32
	s_mul_i32 s72, s62, 5
	s_add_i32 s72, s72, 3
	s_and_b64 s[6:7], s[4:5], s[6:7]
	s_mov_b64 exec, s[6:7]
	s_cbranch_execz .LBB0_303
	v_readlane_b32 s10, v253, 57
	v_readlane_b32 s11, v253, 58
	v_readlane_b32 s73, v254, 38
	v_mov_b32_e32 v2, 1
	s_nop 4
	global_atomic_add v3, v1, v2, s[10:11] sc0
	v_mov_b32_e32 v0, s73
	v_readlane_b32 s73, v254, 39
	ds_read_b32 v4, v0
	s_nop 1
	v_mov_b32_e32 v0, s73
	ds_read_b32 v5, v0
	s_waitcnt lgkmcnt(0)
	v_mul_lo_u32 v4, v4, s72
	v_mul_lo_u32 v5, v5, s72
	s_waitcnt vmcnt(0)
	v_add_u32_e32 v3, 1, v3
	v_cmp_eq_u32_e32 vcc, v3, v4
	s_cbranch_vccz .Lxb2_poll
	buffer_wbl2 sc1
	v_readlane_b32 s10, v253, 61
	v_readlane_b32 s11, v253, 62
	s_waitcnt vmcnt(0)
	s_nop 4
	global_atomic_add v3, v1, v2, s[10:11] sc0
	s_waitcnt vmcnt(0)
	v_add_u32_e32 v3, 1, v3
	v_cmp_eq_u32_e32 vcc, v3, v5
	s_cbranch_vccz .Lxb2_poll
	s_add_u32 s10, s30, 0x8400
	s_addc_u32 s11, s31, 0
	s_mov_b64 exec, -1
	v_mbcnt_lo_u32_b32 v3, -1, 0
	v_mbcnt_hi_u32_b32 v3, -1, v3
	s_sub_u32 s73, s72, 1
	v_mov_b32_e32 v2, s73
	v_lshlrev_b32_e32 v3, 5, v3
	s_nop 1
	global_store_dword v3, v2, s[10:11] sc0 sc1
	global_store_dword v3, v2, s[10:11] offset:2048 sc0 sc1
	s_add_u32 s10, s10, 0x1000
	s_addc_u32 s11, s11, 0
	global_store_dword v3, v2, s[10:11] sc0 sc1
	global_store_dword v3, v2, s[10:11] offset:2048 sc0 sc1
	s_mov_b64 exec, s[6:7]

.Lp3_setup:
	v_mov_b32_e32 v178, v194
	v_readlane_b32 s6, v252, 47
	v_readfirstlane_b32 s4, v178
	s_waitcnt vmcnt(0)
	v_and_b32_e32 v2, 63, v178
	s_ashr_i32 s14, s4, 6
	v_lshl_add_u32 v4, v2, 3, s14
	v_ashrrev_i32_e32 v5, 31, v4
	v_readlane_b32 s7, v252, 48
	v_and_b32_e32 v0, 64, v198
	s_and_b32 s4, s4, 0x3fffffc0
	v_lshl_add_u64 v[4:5], v[4:5], 2, s[6:7]
	global_load_dword v3, v[4:5], off
	v_add_u32_e32 v4, -1, v198
	v_cmp_lt_i32_e32 vcc, v4, v0
	v_add_u32_e32 v5, -2, v198
	v_cmp_gt_u32_e64 s[36:37], 32, v2
	v_cndmask_b32_e32 v4, v4, v198, vcc
	v_lshlrev_b32_e32 v4, 2, v4
	v_cmp_eq_u32_e32 vcc, 0, v2
	s_lshl_b32 s4, s4, 2
	s_add_i32 s4, s4, 0
	v_cmp_eq_u32_e64 s[38:39], 0, v178
	s_waitcnt vmcnt(0)
	ds_bpermute_b32 v4, v4, v3
	s_waitcnt lgkmcnt(0)
	v_add_f32_e32 v4, v3, v4
	v_cndmask_b32_e32 v4, v4, v3, vcc
	v_cmp_lt_i32_e32 vcc, v5, v0
	s_nop 1
	v_cndmask_b32_e32 v5, v5, v198, vcc
	v_lshlrev_b32_e32 v5, 2, v5
	ds_bpermute_b32 v5, v5, v4
	v_cmp_gt_u32_e32 vcc, 2, v2
	s_waitcnt lgkmcnt(0)
	v_add_f32_e32 v5, v4, v5
	v_cndmask_b32_e32 v4, v5, v4, vcc
	v_add_u32_e32 v5, -4, v198
	v_cmp_lt_i32_e32 vcc, v5, v0
	s_nop 1
	v_cndmask_b32_e32 v5, v5, v198, vcc
	v_lshlrev_b32_e32 v5, 2, v5
	ds_bpermute_b32 v5, v5, v4
	v_cmp_gt_u32_e32 vcc, 4, v2
	s_waitcnt lgkmcnt(0)
	v_add_f32_e32 v5, v4, v5
	v_cndmask_b32_e32 v4, v5, v4, vcc
	v_add_u32_e32 v5, -8, v198
	v_cmp_lt_i32_e32 vcc, v5, v0
	s_nop 1
	v_cndmask_b32_e32 v5, v5, v198, vcc
	v_lshlrev_b32_e32 v5, 2, v5
	ds_bpermute_b32 v5, v5, v4
	v_cmp_gt_u32_e32 vcc, 8, v2
	s_waitcnt lgkmcnt(0)
	v_add_f32_e32 v5, v4, v5
	v_cndmask_b32_e32 v4, v5, v4, vcc
	v_add_u32_e32 v5, -16, v198
	v_cmp_lt_i32_e32 vcc, v5, v0
	s_nop 1
	v_cndmask_b32_e32 v5, v5, v198, vcc
	v_lshlrev_b32_e32 v5, 2, v5
	ds_bpermute_b32 v5, v5, v4
	v_cmp_gt_u32_e32 vcc, 16, v2
	s_waitcnt lgkmcnt(0)
	v_add_f32_e32 v5, v4, v5
	v_cndmask_b32_e32 v4, v5, v4, vcc
	v_subrev_u32_e32 v5, 32, v198
	v_cmp_lt_i32_e32 vcc, v5, v0
	s_nop 1
	v_cndmask_b32_e32 v5, v5, v198, vcc
	v_lshlrev_b32_e32 v5, 2, v5
	ds_bpermute_b32 v5, v5, v4
	s_waitcnt lgkmcnt(0)
	v_add_f32_e32 v5, v4, v5
	v_cndmask_b32_e64 v4, v5, v4, s[36:37]
	v_sub_f32_e32 v3, v4, v3
	v_lshl_add_u32 v4, v2, 2, s4
	v_add_u32_e32 v4, 0x20400, v4
	ds_write_b32 v4, v3
	s_mov_b64 s[52:53], 0x1b800000
	s_cmp_lg_u32 s14, 0
	s_cbranch_scc1 .LBB0_313
	v_lshlrev_b32_e32 v5, 2, v2
	global_load_dword v6, v5, s[20:21]
	global_load_dword v7, v5, s[18:19]
	global_load_dword v8, v5, s[96:97]
	global_load_dword v9, v5, s[94:95]
	s_waitcnt vmcnt(0)
	v_and_b32_e32 v6, 0x7fffffff, v6
	v_and_b32_e32 v7, 0x7fffffff, v7
	v_and_b32_e32 v8, 0x7fffffff, v8
	v_and_b32_e32 v9, 0x7fffffff, v9
	ds_swizzle_b32 v10, v6 offset:0x041F
	ds_swizzle_b32 v11, v7 offset:0x041F
	ds_swizzle_b32 v12, v8 offset:0x041F
	ds_swizzle_b32 v13, v9 offset:0x041F
	s_waitcnt lgkmcnt(0)
	v_max_f32_e32 v6, v6, v10
	v_max_f32_e32 v7, v7, v11
	v_max_f32_e32 v8, v8, v12
	v_max_f32_e32 v9, v9, v13
	ds_swizzle_b32 v10, v6 offset:0x081F
	ds_swizzle_b32 v11, v7 offset:0x081F
	ds_swizzle_b32 v12, v8 offset:0x081F
	ds_swizzle_b32 v13, v9 offset:0x081F
	s_waitcnt lgkmcnt(0)
	v_max_f32_e32 v6, v6, v10
	v_max_f32_e32 v7, v7, v11
	v_max_f32_e32 v8, v8, v12
	v_max_f32_e32 v9, v9, v13
	ds_swizzle_b32 v10, v6 offset:0x101F
	ds_swizzle_b32 v11, v7 offset:0x101F
	ds_swizzle_b32 v12, v8 offset:0x101F
	ds_swizzle_b32 v13, v9 offset:0x101F
	s_waitcnt lgkmcnt(0)
	v_max_f32_e32 v6, v6, v10
	v_max_f32_e32 v7, v7, v11
	v_max_f32_e32 v8, v8, v12
	v_max_f32_e32 v9, v9, v13
	ds_swizzle_b32 v10, v6 offset:0x201F
	ds_swizzle_b32 v11, v7 offset:0x201F
	ds_swizzle_b32 v12, v8 offset:0x201F
	ds_swizzle_b32 v13, v9 offset:0x201F
	s_waitcnt lgkmcnt(0)
	v_max_f32_e32 v6, v6, v10
	v_max_f32_e32 v7, v7, v11
	v_max_f32_e32 v8, v8, v12
	v_max_f32_e32 v9, v9, v13
	ds_swizzle_b32 v10, v6 offset:0x401F
	ds_swizzle_b32 v11, v7 offset:0x401F
	ds_swizzle_b32 v12, v8 offset:0x401F
	ds_swizzle_b32 v13, v9 offset:0x401F
	s_waitcnt lgkmcnt(0)
	v_max_f32_e32 v6, v6, v10
	v_max_f32_e32 v7, v7, v11
	v_max_f32_e32 v8, v8, v12
	v_max_f32_e32 v9, v9, v13
	s_nop 1
	v_readlane_b32 s6, v6, 0
	v_readlane_b32 s7, v6, 32
	v_readlane_b32 s8, v7, 0
	v_readlane_b32 s9, v7, 32
	v_readlane_b32 s24, v8, 0
	v_readlane_b32 s25, v8, 32
	v_readlane_b32 s40, v9, 0
	v_readlane_b32 s41, v9, 32
	s_nop 1
	v_mov_b32_e32 v10, s7
	v_mov_b32_e32 v11, s9
	v_mov_b32_e32 v12, s25
	v_mov_b32_e32 v13, s41
	v_max_f32_e32 v4, s6, v10
	v_max_f32_e32 v3, s8, v11
	v_mul_f32_e32 v4, 0x41040000, v4
	v_mul_f32_e32 v3, v4, v3
	v_readlane_b32 s6, v254, 41
	v_mul_f32_e32 v3, 0x3fb8aa3b, v3
	s_nop 0
	v_mov_b32_e32 v4, s6
	ds_write_b32 v4, v3
	v_max_f32_e32 v4, s24, v12
	v_max_f32_e32 v3, s40, v13
	v_mul_f32_e32 v4, 0x41040000, v4
	v_mul_f32_e32 v3, v4, v3
	v_readlane_b32 s6, v254, 42
	v_mul_f32_e32 v3, 0x3fb8aa3b, v3
	s_nop 0
	v_mov_b32_e32 v4, s6
	ds_write_b32 v4, v3

.LBB0_322:
	s_or_b64 exec, exec, s[4:5]
	v_lshrrev_b32_e32 v8, 5, v2
	v_lshlrev_b32_e32 v182, 2, v8
	v_and_b32_e32 v183, 31, v178
	v_or_b32_e32 v214, 3, v182
	v_cmp_lt_u32_e64 s[6:7], v214, v183
	v_or_b32_e32 v215, 8, v182
	v_or_b32_e32 v216, 9, v182
	v_writelane_b32 v254, s6, 50
	v_or_b32_e32 v217, 10, v182
	v_or_b32_e32 v218, 11, v182
	v_writelane_b32 v254, s7, 51
	v_cmp_lt_u32_e64 s[6:7], v215, v183
	v_or_b32_e32 v219, 16, v182
	v_or_b32_e32 v220, 17, v182
	v_writelane_b32 v254, s6, 52
	v_or_b32_e32 v221, 18, v182
	v_or_b32_e32 v222, 19, v182
	v_writelane_b32 v254, s7, 53
	v_cmp_lt_u32_e64 s[6:7], v216, v183
	s_mov_b32 s63, s15
	v_or_b32_e32 v223, 24, v182
	v_writelane_b32 v254, s6, 54
	s_lshl_b64 s[4:5], s[62:63], 2
	v_lshrrev_b32_e32 v10, 3, v178
	v_writelane_b32 v254, s7, 55
	v_cmp_lt_u32_e64 s[6:7], v217, v183
	s_add_u32 s24, s30, s4
	v_lshlrev_b32_e32 v176, 3, v8
	v_writelane_b32 v254, s6, 56
	v_lshlrev_b32_e32 v210, 4, v8
	v_and_b32_e32 v10, 4, v10
	v_writelane_b32 v254, s7, 57
	v_cmp_lt_u32_e64 s[6:7], v218, v183
	v_bfe_u32 v11, v178, 2, 2
	v_or_b32_e32 v224, 25, v182
	v_writelane_b32 v254, s6, 58
	v_lshrrev_b32_e32 v8, 1, v178
	s_addc_u32 s25, s31, s5
	v_writelane_b32 v254, s7, 59
	v_cmp_lt_u32_e64 s[6:7], v219, v183
	s_lshl_b32 s46, s14, 5
	v_and_b32_e32 v14, 16, v178
	v_writelane_b32 v254, s6, 60
	v_lshlrev_b32_e32 v2, 2, v2
	v_and_b32_e32 v227, 16, v8
	v_writelane_b32 v254, s7, 61
	v_cmp_lt_u32_e64 s[6:7], v220, v183
	v_or_b32_e32 v8, v11, v10
	v_and_or_b32 v2, v2, 12, v14
	v_writelane_b32 v254, s6, 62
	v_or_b32_e32 v225, 26, v182
	s_add_i32 s4, s46, 32
	v_writelane_b32 v254, s7, 63
	v_cmp_lt_u32_e64 s[6:7], v221, v183
	v_or_b32_e32 v14, 16, v8
	v_lshlrev_b32_e32 v211, 1, v2
	v_writelane_b32 v255, s6, 0
	v_or_b32_e32 v2, s4, v183
	v_or_b32_e32 v15, s4, v8
	v_writelane_b32 v255, s7, 1
	v_cmp_lt_u32_e64 s[6:7], v222, v183
	v_or_b32_e32 v16, s4, v14
	s_add_i32 s4, s46, 64
	v_writelane_b32 v255, s6, 2
	v_or_b32_e32 v226, 27, v182
	v_or_b32_e32 v17, s4, v8
	v_writelane_b32 v255, s7, 3
	v_cmp_lt_u32_e64 s[6:7], v223, v183
	v_or_b32_e32 v18, s4, v14
	s_add_i32 s4, s46, 0x60
	v_writelane_b32 v255, s6, 4
	v_or_b32_e32 v209, s46, v183
	v_or_b32_e32 v19, s4, v8
	v_writelane_b32 v255, s7, 5
	v_cmp_lt_u32_e64 s[6:7], v224, v183
	v_or_b32_e32 v14, s4, v14
	s_add_i32 s4, s46, 0x80
	v_writelane_b32 v255, s6, 6
	v_ashrrev_i32_e32 v205, 3, v178
	s_movk_i32 s5, 0x90
	v_writelane_b32 v255, s7, 7
	v_cmp_lt_u32_e64 s[6:7], v225, v183
	v_subrev_u32_e32 v20, s46, v209
	v_or_b32_e32 v21, s4, v183
	v_writelane_b32 v255, s6, 8
	v_or3_b32 v22, v10, s4, v11
	s_add_i32 s4, s46, 0x90
	v_writelane_b32 v255, s7, 9
	v_cmp_lt_u32_e64 s[6:7], v226, v183
	v_mul_lo_u32 v207, v205, s5
	v_mul_lo_u32 v9, v209, s5
	v_writelane_b32 v255, s6, 10
	v_or3_b32 v12, v10, s46, v11
	v_mul_lo_u32 v2, v2, s5
	v_writelane_b32 v255, s7, 11
	v_mul_lo_u32 v21, v21, s5
	v_or3_b32 v10, s4, v10, v11
	v_cmp_gt_i32_e64 s[4:5], v182, v20
	v_or_b32_e32 v213, 2, v182
	v_xor_b32_e32 v4, 32, v198
	v_writelane_b32 v255, s4, 12
	v_add_u32_e32 v0, 64, v0
	v_cmp_lt_i32_e32 vcc, v4, v0
	v_writelane_b32 v255, s5, 13
	v_cmp_gt_i32_e64 s[4:5], v213, v20
	v_cndmask_b32_e32 v0, v198, v4, vcc
	v_lshlrev_b32_e32 v179, 2, v0
	v_writelane_b32 v255, s4, 14
	v_lshlrev_b32_e32 v0, 4, v178
	v_mul_u32_u24_e32 v230, 0xc0, v8
	v_writelane_b32 v255, s5, 15
	v_cmp_gt_i32_e64 s[4:5], v214, v20
	v_and_b32_e32 v8, 3, v178
	v_and_b32_e32 v0, 0x70, v0
	v_writelane_b32 v255, s4, 16
	v_mul_lo_u32 v208, v205, s23
	v_mul_lo_u32 v12, v12, s23
	v_writelane_b32 v255, s5, 17
	v_cmp_gt_i32_e64 s[4:5], v215, v20
	v_mul_lo_u32 v15, v15, s23
	v_mul_lo_u32 v16, v16, s23
	v_writelane_b32 v255, s4, 18
	v_mul_lo_u32 v17, v17, s23
	v_mul_lo_u32 v18, v18, s23
	v_writelane_b32 v255, s5, 19
	v_cmp_gt_i32_e64 s[4:5], v216, v20
	v_mul_lo_u32 v19, v19, s23
	v_mul_lo_u32 v14, v14, s23
	v_writelane_b32 v255, s4, 20
	v_mul_lo_u32 v22, v22, s23
	v_mul_lo_u32 v10, v10, s23
	v_writelane_b32 v255, s5, 21
	v_cmp_gt_i32_e64 s[4:5], v217, v20
	v_and_b32_e32 v3, 32, v3
	v_lshlrev_b32_e32 v8, 3, v8
	v_lshl_add_u64 v[180:181], s[0:1], 0, v[0:1]
	v_add_u32_e32 v206, 0, v0
	v_add_u32_e32 v0, 0x3000, v208
	v_add_u32_e32 v4, 0x6000, v208
	v_add_u32_e32 v5, 0x9000, v208
	v_add_u32_e32 v6, 0xc000, v208
	v_add_u32_e32 v7, 0xf000, v208
	v_add_u32_e32 v9, 0, v9
	v_add_u32_e32 v13, 0, v12
	v_or_b32_e32 v212, 1, v182
	v_add_u32_e32 v2, 0, v2
	v_add_u32_e32 v15, 0, v15
	v_add_u32_e32 v16, 0, v16
	v_add_u32_e32 v17, 0, v17
	v_add_u32_e32 v18, 0, v18
	v_add_u32_e32 v19, 0, v19
	v_add_u32_e32 v14, 0, v14
	v_add_u32_e32 v21, 0, v21
	v_add_u32_e32 v22, 0, v22
	v_add_u32_e32 v10, 0, v10
	v_writelane_b32 v255, s4, 22
	s_movk_i32 s6, 0x80
	v_mul_u32_u24_e32 v229, 0x90, v183
	v_or3_b32 v231, v12, v3, v8
	s_mulk_i32 s14, 0x1200
	v_max_i32_e32 v3, 0x80, v209
	s_mov_b32 s70, s62
	v_cmp_lt_u32_e64 s[72:73], v182, v183
	v_cmp_lt_u32_e64 s[74:75], v212, v183
	v_cmp_lt_u32_e64 s[78:79], v213, v183
	v_cmp_lt_i32_e64 s[44:45], v182, v20
	v_writelane_b32 v255, s5, 23
	v_cmp_gt_i32_e64 s[56:57], v218, v20
	v_cmp_gt_i32_e64 s[58:59], v219, v20
	v_cmp_gt_i32_e64 s[60:61], v220, v20
	v_cmp_gt_i32_e64 s[62:63], v221, v20
	v_cmp_gt_i32_e64 s[64:65], v222, v20
	v_cmp_gt_i32_e64 s[66:67], v223, v20
	v_cmp_gt_i32_e64 s[40:41], v224, v20
	v_cmp_gt_i32_e64 s[8:9], v225, v20
	v_cmp_gt_i32_e64 s[4:5], v226, v20
	v_cmp_gt_i32_e64 s[6:7], s6, v178
	v_lshlrev_b32_e32 v228, 3, v178
	v_add3_u32 v232, s14, v229, v210
	v_subrev_u32_e32 v233, s46, v3
	s_or_b32 s71, s46, 31
	v_add_u32_e32 v196, v206, v0
	v_add_u32_e32 v202, v206, v4
	v_add_u32_e32 v203, v206, v5
	v_add_u32_e32 v204, v206, v6
	v_add_u32_e32 v238, v206, v7
	v_add_u32_e32 v239, v9, v210
	v_add_u32_e32 v240, v13, v211
	v_add_u32_e32 v241, v2, v227
	v_add_u32_e32 v242, v15, v211
	v_add_u32_e32 v243, v16, v211
	v_add_u32_e32 v244, v17, v211
	v_add_u32_e32 v245, v18, v211
	v_add_u32_e32 v246, v19, v211
	v_add_u32_e32 v247, v14, v211
	v_add_u32_e32 v248, v21, v210
	v_add_u32_e32 v249, v22, v211
	v_add_u32_e32 v250, v10, v211
	s_waitcnt lgkmcnt(0)
	s_barrier
	v_readlane_b32 s14, v255, 41
	s_mov_b32 s32, 0
	s_cmp_eq_u32 s14, 1
	s_cbranch_scc1 .Lb2_first
	s_cmp_eq_u32 s14, 3
	s_cbranch_scc0 .LBB0_325
	s_mov_b32 s14, 0
	s_mov_b32 s32, 1
	v_writelane_b32 v255, s14, 41
	s_branch .LBB0_325
.Lb2_first:
	s_mov_b32 s14, 2
	v_readlane_b32 s42, v252, 0
	v_writelane_b32 v255, s14, 41
	s_addk_i32 s42, 0x648
	s_branch .Lq_aunit
.Lb2_wait:
	s_mov_b32 s14, 3
	s_mov_b64 s[86:87], exec
	v_writelane_b32 v255, s14, 41
	s_and_b64 exec, exec, s[38:39]
	s_cbranch_execz .Lb2w_done
	v_readlane_b32 s10, v252, 0
	s_mul_i32 s14, s70, 5
	s_add_i32 s14, s14, 2
	s_lshl_b32 s10, s10, 5
	s_add_u32 s10, s10, 0x8400
	s_add_u32 s10, s30, s10
	s_addc_u32 s11, s31, 0
.Lb2w_spin:
	global_load_dword v3, v1, s[10:11] sc1
	s_waitcnt vmcnt(0)
	v_cmp_le_u32_e32 vcc, s14, v3
	s_cbranch_vccnz .Lb2w_acq
	s_sleep 1
	s_branch .Lb2w_spin

.Lb2w_done:
	s_mov_b64 exec, s[86:87]
	s_waitcnt vmcnt(0) lgkmcnt(0)
	s_barrier
	s_mov_b32 s62, s70
	s_branch .Lp3_setup

.LBB0_325:
	v_readlane_b32 s14, v255, 41
	s_nop 0
	s_cmp_eq_u32 s14, 2
	s_cbranch_scc1 .Lb2_wait

.LBB0_329:
	s_or_b64 exec, exec, s[10:11]
	s_lshl_b32 s14, s32, 1
	s_and_b32 s14, s14, 4
	s_add_i32 s14, s14, 0x20040
	v_mov_b32_e32 v2, s14
	s_and_b32 s32, s32, 2
	s_xor_b32 s32, s32, 2
	s_waitcnt lgkmcnt(0)
	s_barrier
	ds_read_b32 v0, v2
	s_mov_b64 s[10:11], -1
	s_waitcnt lgkmcnt(0)
	v_readfirstlane_b32 s42, v0
	s_movk_i32 s14, 0x747
	s_cmp_eq_u32 s3, 0x100
	s_cselect_b32 s14, 0x647, s14
	s_cmp_gt_i32 s42, s14
	s_cbranch_scc1 .LBB0_324
	s_cmpk_gt_i32 s42, 0x47
	s_cbranch_scc0 .LBB0_405
	s_cmpk_gt_u32 s42, 0x2c7
	s_cbranch_scc0 .LBB0_346
.Lq_aunit:
	s_mov_b64 s[10:11], exec
	s_and_b64 exec, exec, s[38:39]
	s_cbranch_execz .Lq_noissue
	v_mov_b32_e32 v165, 1
	global_atomic_add v164, v1, v165, s[24:25] sc0
